# c7_diff_interleaved_exps
# speedup vs baseline: 1.0211x; 1.0084x over previous
.Lf_odd_exp:
	v_exp_f32_e32 v82, v114
	v_exp_f32_e32 v83, v115
	ds_read_b64_tr_b16 v[114:115], v1 offset:0x200
	v_exp_f32_e32 v84, v116
	v_exp_f32_e32 v85, v117
	ds_read_b64_tr_b16 v[116:117], v1 offset:0xa00
	v_exp_f32_e32 v86, v118
	v_exp_f32_e32 v87, v119
	ds_read_b64_tr_b16 v[118:119], v1 offset:0x1200
	v_exp_f32_e32 v88, v120
	v_exp_f32_e32 v89, v121
	ds_read_b64_tr_b16 v[120:121], v1 offset:0x1a00
	v_exp_f32_e32 v90, v122
	v_exp_f32_e32 v91, v123
	ds_read_b64_tr_b16 v[122:123], v1 offset:0x2200
	v_exp_f32_e32 v92, v124
	v_exp_f32_e32 v93, v125
	ds_read_b64_tr_b16 v[124:125], v1 offset:0x2a00
	v_exp_f32_e32 v98, v130
	v_exp_f32_e32 v99, v131
	ds_read_b64_tr_b16 v[130:131], v1 offset:0x3200
	v_exp_f32_e32 v100, v132
	v_exp_f32_e32 v101, v133
	ds_read_b64_tr_b16 v[132:133], v1 offset:0x3a00
	s_waitcnt lgkmcnt(8)
	v_mfma_f32_32x32x16_bf16 v[64:79], v[166:169], v[182:185], v[64:79]
	v_exp_f32_e32 v94, v126
	v_exp_f32_e32 v95, v127
	v_exp_f32_e32 v96, v128
	v_mfma_f32_32x32x16_bf16 v[64:79], v[12:15], v[178:181], v[64:79]
	v_exp_f32_e32 v97, v129
	v_exp_f32_e32 v102, v134
	v_exp_f32_e32 v103, v135
	v_mfma_f32_32x32x16_bf16 v[64:79], v[8:11], v[174:177], v[64:79]
	v_exp_f32_e32 v104, v136
	v_exp_f32_e32 v105, v137
	v_exp_f32_e32 v106, v138
	v_mfma_f32_32x32x16_bf16 v[64:79], v[4:7], v[170:173], v[64:79]
	v_exp_f32_e32 v107, v139
	v_exp_f32_e32 v108, v140
	v_exp_f32_e32 v109, v141
	ds_read_b64_tr_b16 v[126:127], v1 offset:0x400
	ds_read_b64_tr_b16 v[128:129], v1 offset:0xc00
	ds_read_b64_tr_b16 v[134:135], v1 offset:0x1400
	ds_read_b64_tr_b16 v[136:137], v1 offset:0x1c00
	ds_read_b64_tr_b16 v[138:139], v1 offset:0x2400
	ds_read_b64_tr_b16 v[140:141], v1 offset:0x2c00
	ds_read_b64_tr_b16 v[170:171], v1 offset:0x3400
	ds_read_b64_tr_b16 v[172:173], v1 offset:0x3c00
	s_waitcnt lgkmcnt(8)
	v_mfma_f32_32x32x16_bf16 v[48:63], v[166:169], v[114:117], v[48:63]
	v_exp_f32_e32 v80, v112
	v_mfma_f32_32x32x16_bf16 v[48:63], v[12:15], v[118:121], v[48:63]
	v_exp_f32_e32 v81, v113
	v_mfma_f32_32x32x16_bf16 v[48:63], v[8:11], v[122:125], v[48:63]
	v_exp_f32_e32 v110, v142
	v_mfma_f32_32x32x16_bf16 v[48:63], v[4:7], v[130:133], v[48:63]
	v_exp_f32_e32 v111, v143
	ds_read_b64_tr_b16 v[112:113], v1 offset:0x600
	ds_read_b64_tr_b16 v[114:115], v1 offset:0xe00
	ds_read_b64_tr_b16 v[116:117], v1 offset:0x1600
	ds_read_b64_tr_b16 v[118:119], v1 offset:0x1e00
	ds_read_b64_tr_b16 v[120:121], v1 offset:0x2600
	ds_read_b64_tr_b16 v[122:123], v1 offset:0x2e00
	ds_read_b64_tr_b16 v[130:131], v1 offset:0x3600
	ds_read_b64_tr_b16 v[132:133], v1 offset:0x3e00
	s_waitcnt lgkmcnt(8)
	v_mfma_f32_32x32x16_bf16 v[32:47], v[166:169], v[126:129], v[32:47]
	v_mfma_f32_32x32x16_bf16 v[32:47], v[12:15], v[134:137], v[32:47]
	v_mfma_f32_32x32x16_bf16 v[32:47], v[8:11], v[138:141], v[32:47]
	v_mfma_f32_32x32x16_bf16 v[32:47], v[4:7], v[170:173], v[32:47]
	s_waitcnt lgkmcnt(0)
	v_mfma_f32_32x32x16_bf16 v[16:31], v[166:169], v[112:115], v[16:31]
	v_mfma_f32_32x32x16_bf16 v[16:31], v[12:15], v[116:119], v[16:31]
	v_mfma_f32_32x32x16_bf16 v[16:31], v[8:11], v[120:123], v[16:31]
	v_mfma_f32_32x32x16_bf16 v[16:31], v[4:7], v[130:133], v[16:31]
	s_branch .Lresc_odd

.Lf_even_exp:
	v_exp_f32_e32 v82, v114
	v_exp_f32_e32 v83, v115
	ds_read_b64_tr_b16 v[114:115], v162 offset:0x200
	v_exp_f32_e32 v84, v116
	v_exp_f32_e32 v85, v117
	ds_read_b64_tr_b16 v[116:117], v162 offset:0xa00
	v_exp_f32_e32 v86, v118
	v_exp_f32_e32 v87, v119
	ds_read_b64_tr_b16 v[118:119], v162 offset:0x1200
	v_exp_f32_e32 v88, v120
	v_exp_f32_e32 v89, v121
	ds_read_b64_tr_b16 v[120:121], v162 offset:0x1a00
	v_exp_f32_e32 v90, v122
	v_exp_f32_e32 v91, v123
	ds_read_b64_tr_b16 v[122:123], v162 offset:0x2200
	v_exp_f32_e32 v92, v124
	v_exp_f32_e32 v93, v125
	ds_read_b64_tr_b16 v[124:125], v162 offset:0x2a00
	v_exp_f32_e32 v98, v130
	v_exp_f32_e32 v99, v131
	ds_read_b64_tr_b16 v[130:131], v162 offset:0x3200
	v_exp_f32_e32 v100, v132
	v_exp_f32_e32 v101, v133
	ds_read_b64_tr_b16 v[132:133], v162 offset:0x3a00
	s_waitcnt lgkmcnt(8)
	v_mfma_f32_32x32x16_bf16 v[64:79], v[166:169], v[182:185], v[64:79]
	v_exp_f32_e32 v94, v126
	v_exp_f32_e32 v95, v127
	v_exp_f32_e32 v96, v128
	v_mfma_f32_32x32x16_bf16 v[64:79], v[12:15], v[178:181], v[64:79]
	v_exp_f32_e32 v97, v129
	v_exp_f32_e32 v102, v134
	v_exp_f32_e32 v103, v135
	v_mfma_f32_32x32x16_bf16 v[64:79], v[8:11], v[174:177], v[64:79]
	v_exp_f32_e32 v104, v136
	v_exp_f32_e32 v105, v137
	v_exp_f32_e32 v106, v138
	v_mfma_f32_32x32x16_bf16 v[64:79], v[4:7], v[170:173], v[64:79]
	v_exp_f32_e32 v107, v139
	v_exp_f32_e32 v108, v140
	v_exp_f32_e32 v109, v141
	ds_read_b64_tr_b16 v[126:127], v162 offset:0x400
	ds_read_b64_tr_b16 v[128:129], v162 offset:0xc00
	ds_read_b64_tr_b16 v[134:135], v162 offset:0x1400
	ds_read_b64_tr_b16 v[136:137], v162 offset:0x1c00
	ds_read_b64_tr_b16 v[138:139], v162 offset:0x2400
	ds_read_b64_tr_b16 v[140:141], v162 offset:0x2c00
	ds_read_b64_tr_b16 v[170:171], v162 offset:0x3400
	ds_read_b64_tr_b16 v[172:173], v162 offset:0x3c00
	s_waitcnt lgkmcnt(8)
	v_mfma_f32_32x32x16_bf16 v[48:63], v[166:169], v[114:117], v[48:63]
	v_exp_f32_e32 v80, v112
	v_mfma_f32_32x32x16_bf16 v[48:63], v[12:15], v[118:121], v[48:63]
	v_exp_f32_e32 v81, v113
	v_mfma_f32_32x32x16_bf16 v[48:63], v[8:11], v[122:125], v[48:63]
	v_exp_f32_e32 v110, v142
	v_mfma_f32_32x32x16_bf16 v[48:63], v[4:7], v[130:133], v[48:63]
	v_exp_f32_e32 v111, v143
	ds_read_b64_tr_b16 v[112:113], v162 offset:0x600
	ds_read_b64_tr_b16 v[114:115], v162 offset:0xe00
	ds_read_b64_tr_b16 v[116:117], v162 offset:0x1600
	ds_read_b64_tr_b16 v[118:119], v162 offset:0x1e00
	ds_read_b64_tr_b16 v[120:121], v162 offset:0x2600
	ds_read_b64_tr_b16 v[122:123], v162 offset:0x2e00
	ds_read_b64_tr_b16 v[130:131], v162 offset:0x3600
	ds_read_b64_tr_b16 v[132:133], v162 offset:0x3e00
	s_waitcnt lgkmcnt(8)
	v_mfma_f32_32x32x16_bf16 v[32:47], v[166:169], v[126:129], v[32:47]
	v_mfma_f32_32x32x16_bf16 v[32:47], v[12:15], v[134:137], v[32:47]
	v_mfma_f32_32x32x16_bf16 v[32:47], v[8:11], v[138:141], v[32:47]
	v_mfma_f32_32x32x16_bf16 v[32:47], v[4:7], v[170:173], v[32:47]
	s_waitcnt lgkmcnt(0)
	v_mfma_f32_32x32x16_bf16 v[16:31], v[166:169], v[112:115], v[16:31]
	v_mfma_f32_32x32x16_bf16 v[16:31], v[12:15], v[116:119], v[16:31]
	v_mfma_f32_32x32x16_bf16 v[16:31], v[8:11], v[120:123], v[16:31]
	v_mfma_f32_32x32x16_bf16 v[16:31], v[4:7], v[130:133], v[16:31]
	s_branch .Lresc_even
